# V^T LDS tile re-laid out (144-byte rows, permuted 16-key groups) so every PV fragment is one ds_read_b128
# baseline (speedup 1.0000x reference)
; #define GAS __attribute__((address_space(1)))
; __device__ __forceinline__ void dsa_unit32(const Args& a, LAS unsigned char* lds, const LAS unsigned long long* maskl, int b, int qb, int tid, int wave, int lane) {
;     ...
;     const float negB = -1.01f * 11.313708498984761f * sqrtf(qs);
;     const int nkt = (t0 + 32 + 63) >> 6;
;     f32x16 O[4];
; #pragma unroll
;     for (int ct = 0; ct < 4; ++ct)
; #pragma unroll
;         for (int i = 0; i < 16; ++i) O[ct][i] = 0.f;
;     float l = 0.f;
;     u32x4 rk0[2], rv0[2], rk1[2], rv1[2];
;     const unsigned vok0 = (unsigned)((tid >> 4) * 128 + 8 * (tid & 15)) * 2u, vok1 = vok0 + 32u * 128u * 2u;
;     const unsigned vov0 = (unsigned)((tid >> 3) * SEQ + 8 * (tid & 7)) * 2u, vov1 = vov0 + 64u * (unsigned)SEQ * 2u;
;     const GAS char* ckb = (const GAS char*)ckv + (size_t)rowb * 256; const GAS char* cvb = (const GAS char*)ckvT + (size_t)b * 128 * SEQ * 2;
.LBB0_1300:
	s_waitcnt lgkmcnt(0)
	v_add_f32_e32 v17, v17, v18
	s_mov_b32 s0, 0xf800000
	v_mul_f32_e32 v18, 0x4f800000, v17
	v_cmp_gt_f32_e32 vcc, s0, v17
	v_and_b32_e32 v195, 6, v15
	v_lshlrev_b32_e32 v195, 4, v195
	v_and_b32_e32 v20, 1, v15
	v_lshl_or_b32 v195, v20, 3, v195
	v_lshrrev_b32_e32 v16, 4, v15
	v_cndmask_b32_e32 v17, v17, v18, vcc
	v_sqrt_f32_e32 v18, v17
	s_movk_i32 s0, 0x110
	v_mul_lo_u32 v16, v16, s0
	s_movk_i32 s1, 0x90
	v_add_u32_e32 v20, -1, v18
	v_fma_f32 v21, -v20, v18, v17
	v_cmp_ge_f32_e64 s[6:7], 0, v21
	v_add_u32_e32 v21, 1, v18
	v_mad_u32_u24 v202, v5, s0, 0
	v_cndmask_b32_e64 v20, v18, v20, s[6:7]
	v_fma_f32 v18, -v21, v18, v17
	v_cmp_lt_f32_e64 s[6:7], 0, v18
	v_lshlrev_b32_e32 v19, 4, v14
	v_lshlrev_b32_e32 v182, 2, v14
	v_cndmask_b32_e64 v18, v20, v21, s[6:7]
	v_mul_f32_e32 v20, 0x37800000, v18
	v_cndmask_b32_e32 v18, v18, v20, vcc
	v_cmp_class_f32_e32 vcc, v17, v185
	v_mov_b32_e32 v194, 0
	s_addk_i32 s4, 0x5f
	v_cndmask_b32_e32 v17, v18, v17, vcc
	v_mul_f32_e32 v70, 0xc136d45c, v17
	v_and_b32_e32 v17, 0xf0, v6
	v_add_u32_e32 v17, 0, v17
	v_add_u32_e32 v196, v17, v16
	v_lshrrev_b32_e32 v16, 3, v15
	v_add_u32_e32 v15, 0x200, v15
	v_mul_lo_u32 v197, v16, s1
	v_lshrrev_b32_e32 v16, 4, v15
	v_mul_lo_u32 v16, v16, s0
	v_lshrrev_b32_e32 v15, 3, v15
	s_movk_i32 s0, 0xff80
	v_mul_lo_u32 v200, v15, s1
	v_mad_i32_i24 v14, v5, s0, v202
	v_readlane_b32 s0, v254, 28
	v_readlane_b32 s1, v254, 29
	s_movk_i32 s2, 0x4400
	v_add_u32_e32 v203, v14, v19
	v_add_u32_e32 v14, 0xd400, v14
	v_lshl_add_u64 v[186:187], s[0:1], 0, v[12:13]
	v_lshl_add_u64 v[188:189], s[0:1], 0, v[10:11]
	v_readlane_b32 s0, v254, 40
	v_mov_b32_e32 v179, v4
	s_lshr_b32 s4, s4, 6
	s_mov_b32 s5, 3
	v_add3_u32 v198, v195, v197, s2
	v_add_u32_e32 v199, v17, v16
	v_add3_u32 v201, v195, v200, s2
	v_mov_b32_e32 v71, v70
	v_mov_b32_e32 v72, v70
	v_mov_b32_e32 v73, v70
	v_mov_b32_e32 v74, v70
	v_mov_b32_e32 v75, v70
	v_mov_b32_e32 v76, v70
	v_mov_b32_e32 v77, v70
	v_mov_b32_e32 v78, v70
	v_mov_b32_e32 v79, v70
	v_mov_b32_e32 v80, v70
	v_mov_b32_e32 v81, v70
	v_mov_b32_e32 v82, v70
	v_mov_b32_e32 v83, v70
	v_mov_b32_e32 v84, v70
	v_mov_b32_e32 v85, v70
	v_or_b32_e32 v184, 32, v182
	v_add_u32_e32 v204, 0xd400, v203
	v_lshl_add_u64 v[190:191], s[8:9], 0, v[8:9]
	v_lshl_add_u64 v[192:193], s[8:9], 0, v[6:7]
	v_lshl_add_u32 v206, v5, 8, s0
	v_mov_b32_e32 v54, 0
	v_mov_b32_e32 v55, v194
	v_mov_b32_e32 v56, v194
	v_mov_b32_e32 v57, v194
	v_mov_b32_e32 v58, v194
	v_mov_b32_e32 v59, v194
	v_mov_b32_e32 v60, v194
	v_mov_b32_e32 v61, v194
	v_mov_b32_e32 v62, v194
	v_mov_b32_e32 v63, v194
	v_mov_b32_e32 v64, v194
	v_mov_b32_e32 v65, v194
	v_mov_b32_e32 v66, v194
	v_mov_b32_e32 v67, v194
	v_mov_b32_e32 v68, v194
	v_mov_b32_e32 v69, v194
	v_mov_b32_e32 v38, 0
	v_mov_b32_e32 v39, v194
	v_mov_b32_e32 v40, v194
	v_mov_b32_e32 v41, v194
	v_mov_b32_e32 v42, v194
	v_mov_b32_e32 v43, v194
	v_mov_b32_e32 v44, v194
	v_mov_b32_e32 v45, v194
	v_mov_b32_e32 v46, v194
	v_mov_b32_e32 v47, v194
	v_mov_b32_e32 v48, v194
	v_mov_b32_e32 v49, v194
	v_mov_b32_e32 v50, v194
	v_mov_b32_e32 v51, v194
	v_mov_b32_e32 v52, v194
	v_mov_b32_e32 v53, v194
	v_mov_b32_e32 v22, 0
	v_mov_b32_e32 v23, v194
	v_mov_b32_e32 v24, v194
	v_mov_b32_e32 v25, v194
	v_mov_b32_e32 v26, v194
	v_mov_b32_e32 v27, v194
	v_mov_b32_e32 v28, v194
	v_mov_b32_e32 v29, v194
	v_mov_b32_e32 v30, v194
	v_mov_b32_e32 v31, v194
	v_mov_b32_e32 v32, v194
	v_mov_b32_e32 v33, v194
	v_mov_b32_e32 v34, v194
	v_mov_b32_e32 v35, v194
	v_mov_b32_e32 v36, v194
	v_mov_b32_e32 v37, v194
	v_mov_b32_e32 v6, 0
	v_mov_b32_e32 v7, v194
	v_mov_b32_e32 v8, v194
	v_mov_b32_e32 v9, v194
	v_mov_b32_e32 v10, v194
	v_mov_b32_e32 v11, v194
	v_mov_b32_e32 v12, v194
	v_mov_b32_e32 v13, v194
	v_mov_b32_e32 v14, v194
	v_mov_b32_e32 v15, v194
	v_mov_b32_e32 v16, v194
	v_mov_b32_e32 v17, v194
	v_mov_b32_e32 v18, v194
	v_mov_b32_e32 v19, v194
	v_mov_b32_e32 v20, v194
	v_mov_b32_e32 v21, v194
	ds_write_b128 v196, v[146:149]
	ds_write2_b64 v198, v[154:155], v[156:157] offset1:2
	ds_write_b128 v199, v[150:153]
	ds_write2_b64 v201, v[158:159], v[160:161] offset1:2
	s_waitcnt lgkmcnt(0)
	s_barrier
	s_branch .LBB0_1302

; #define LAS __attribute__((address_space(3)))
; __device__ __forceinline__ unsigned pk2(float lo, float hi) { f32x2_t v = {lo, hi}; bf16x2_t b = __builtin_convertvector(v, bf16x2_t); return __builtin_bit_cast(unsigned, b); }
; __device__ __forceinline__ void dsa_unit32(const Args& a, LAS unsigned char* lds, const LAS unsigned long long* maskl, int b, int qb, int tid, int wave, int lane) {
;     ...
;     auto compute = [&](int buf, int kt) {
;         const unsigned long long mw = maskl[l31 * 32 + kt];
;         const LAS bf16* Ks = (const LAS bf16*)(lds + buf * STG); const LAS bf16* Vs = (const LAS bf16*)(lds + buf * STG + KBYTES);
;         f32x16 S2[2];
; #pragma unroll
;         for (int kh = 0; kh < 2; ++kh) {
; #pragma unroll
;             for (int i = 0; i < 16; ++i) S2[kh][i] = negB;
;             __builtin_amdgcn_s_setprio(1);
; #pragma unroll
;             for (int ks = 0; ks < 8; ++ks) S2[kh] = mfma32(*(const LAS bf16x8*)(Ks + (32 * kh + l31) * KS + 16 * ks + 8 * hi), qf[ks], S2[kh]);
;             __builtin_amdgcn_s_setprio(0);
;         }
; #pragma unroll
;         for (int kh = 0; kh < 2; ++kh) {
;             const unsigned mh = (unsigned)(mw >> (32 * kh + 4 * hi));
;             float p[16];
; #pragma unroll
;             for (int i = 0; i < 16; ++i) { const float e = __builtin_amdgcn_exp2f(S2[kh][i]);
;                 const int keep = __builtin_amdgcn_sbfe((int)mh, 8 * (i >> 2) + (i & 3), 1);
;                 p[i] = __builtin_bit_cast(float, __builtin_bit_cast(int, e) & keep); l += p[i]; }
;             u32x4 w0, w1;
;             w0.x = pk2(p[0], p[1]); w0.y = pk2(p[2], p[3]); w0.z = pk2(p[4], p[5]); w0.w = pk2(p[6], p[7]);
;             w1.x = pk2(p[8], p[9]); w1.y = pk2(p[10], p[11]); w1.z = pk2(p[12], p[13]); w1.w = pk2(p[14], p[15]);
;             const bf16x8 pa = __builtin_bit_cast(bf16x8, w0), pb = __builtin_bit_cast(bf16x8, w1);
;             __builtin_amdgcn_s_setprio(1);
; #pragma unroll
;             for (int ct = 0; ct < 4; ++ct) {
;                 const LAS bf16* vr = Vs + (32 * ct + l31) * VS + 4 * hi + 32 * kh;
;                 O[ct] = mfma32(cat8(*(const LAS u32x2*)(vr), *(const LAS u32x2*)(vr + 8)), pa, O[ct]);
;                 O[ct] = mfma32(cat8(*(const LAS u32x2*)(vr + 16), *(const LAS u32x2*)(vr + 24)), pb, O[ct]);
;             }
;             __builtin_amdgcn_s_setprio(0);
;         }
;     };
.LBB0_1304:
	s_cmp_lt_u32 s17, 4
	s_cbranch_scc0 .Ldsa_B0
	v_add_u32_e32 v207, -8, v206
	ds_read_b64 v[220:221], v207
	v_add_u32_e32 v207, v202, v180
	ds_read_b128 v[216:219], v207 offset:0
	ds_read_b128 v[228:231], v207 offset:32
	ds_read_b128 v[232:235], v207 offset:64
	ds_read_b128 v[236:239], v207 offset:96
	ds_read_b128 v[240:243], v207 offset:128
	ds_read_b128 v[244:247], v207 offset:160
	ds_read_b128 v[248:251], v207 offset:192
	ds_read_b128 v[222:225], v207 offset:224
	ds_read_b128 v[208:211], v207 offset:8704
	ds_read_b128 v[212:215], v207 offset:8736
	s_setprio 1
	s_waitcnt lgkmcnt(9)
	v_mfma_f32_32x32x16_bf16 v[102:117], v[216:219], v[126:129], v[70:85]
	ds_read_b128 v[216:219], v207 offset:8768
	s_waitcnt lgkmcnt(9)
	v_mfma_f32_32x32x16_bf16 v[102:117], v[228:231], v[0:3], v[102:117]
	ds_read_b128 v[228:231], v207 offset:8800
	s_waitcnt lgkmcnt(9)
	v_mfma_f32_32x32x16_bf16 v[102:117], v[232:235], v[118:121], v[102:117]
	ds_read_b128 v[232:235], v207 offset:8832
	s_waitcnt lgkmcnt(9)
	v_mfma_f32_32x32x16_bf16 v[102:117], v[236:239], v[122:125], v[102:117]
	ds_read_b128 v[236:239], v207 offset:8864
	s_waitcnt lgkmcnt(9)
	v_mfma_f32_32x32x16_bf16 v[102:117], v[240:243], v[130:133], v[102:117]
	ds_read_b128 v[240:243], v207 offset:8896
	s_waitcnt lgkmcnt(9)
	v_mfma_f32_32x32x16_bf16 v[102:117], v[244:247], v[134:137], v[102:117]
	ds_read_b128 v[244:247], v207 offset:8928
	s_waitcnt lgkmcnt(9)
	v_mfma_f32_32x32x16_bf16 v[102:117], v[248:251], v[138:141], v[102:117]
	s_waitcnt lgkmcnt(8)
	v_mfma_f32_32x32x16_bf16 v[102:117], v[222:225], v[142:145], v[102:117]
	s_waitcnt lgkmcnt(7)
	v_mfma_f32_32x32x16_bf16 v[86:101], v[208:211], v[126:129], v[70:85]
	s_waitcnt lgkmcnt(6)
	v_mfma_f32_32x32x16_bf16 v[86:101], v[212:215], v[0:3], v[86:101]
	s_waitcnt lgkmcnt(5)
	v_mfma_f32_32x32x16_bf16 v[86:101], v[216:219], v[118:121], v[86:101]
	ds_read_b128 v[248:251], v203 offset:17408
	ds_read_b128 v[222:225], v203 offset:17440
	ds_read_b128 v[216:219], v203 offset:22016
	s_waitcnt lgkmcnt(7)
	v_mfma_f32_32x32x16_bf16 v[86:101], v[228:231], v[122:125], v[86:101]
	ds_read_b128 v[228:231], v203 offset:22048
	s_waitcnt lgkmcnt(7)
	v_mfma_f32_32x32x16_bf16 v[86:101], v[232:235], v[130:133], v[86:101]
	ds_read_b128 v[232:235], v203 offset:26624
	s_waitcnt lgkmcnt(7)
	v_mfma_f32_32x32x16_bf16 v[86:101], v[236:239], v[134:137], v[86:101]
	ds_read_b128 v[236:239], v203 offset:26656
	s_waitcnt lgkmcnt(7)
	v_mfma_f32_32x32x16_bf16 v[86:101], v[240:243], v[138:141], v[86:101]
	ds_read_b128 v[240:243], v203 offset:31232
	s_waitcnt lgkmcnt(7)
	v_mfma_f32_32x32x16_bf16 v[86:101], v[244:247], v[142:145], v[86:101]
	ds_read_b128 v[244:247], v203 offset:31264
	s_setprio 0
	v_lshrrev_b64 v[208:209], v182, v[220:221]
	v_exp_f32_e32 v102, v102
	v_bfe_i32 v209, v208, 0, 1
	v_exp_f32_e32 v103, v103
	v_bfe_i32 v210, v208, 1, 1
	v_and_b32_e32 v102, v102, v209
	v_exp_f32_e32 v104, v104
	v_bfe_i32 v211, v208, 2, 1
	v_and_b32_e32 v103, v103, v210
	v_exp_f32_e32 v105, v105
	v_bfe_i32 v209, v208, 3, 1
	v_and_b32_e32 v104, v104, v211
	v_exp_f32_e32 v106, v106
	v_bfe_i32 v210, v208, 8, 1
	v_and_b32_e32 v105, v105, v209
	v_exp_f32_e32 v107, v107
	v_bfe_i32 v211, v208, 9, 1
	v_and_b32_e32 v106, v106, v210
	v_exp_f32_e32 v108, v108
	v_bfe_i32 v209, v208, 10, 1
	v_and_b32_e32 v107, v107, v211
	v_exp_f32_e32 v109, v109
	v_bfe_i32 v210, v208, 11, 1
	v_and_b32_e32 v108, v108, v209
	v_exp_f32_e32 v110, v110
	v_bfe_i32 v211, v208, 16, 1
	v_and_b32_e32 v109, v109, v210
	v_exp_f32_e32 v111, v111
	v_bfe_i32 v209, v208, 17, 1
	v_and_b32_e32 v110, v110, v211
	v_exp_f32_e32 v112, v112
	v_bfe_i32 v210, v208, 18, 1
	v_and_b32_e32 v111, v111, v209
	v_exp_f32_e32 v113, v113
	v_bfe_i32 v211, v208, 19, 1
	v_and_b32_e32 v112, v112, v210
	v_exp_f32_e32 v114, v114
	v_bfe_i32 v209, v208, 24, 1
	v_and_b32_e32 v113, v113, v211
	v_exp_f32_e32 v115, v115
	v_bfe_i32 v210, v208, 25, 1
	v_and_b32_e32 v114, v114, v209
	v_exp_f32_e32 v116, v116
	v_bfe_i32 v211, v208, 26, 1
	v_and_b32_e32 v115, v115, v210
	v_exp_f32_e32 v117, v117
	v_bfe_i32 v209, v208, 27, 1
	v_and_b32_e32 v116, v116, v211
	s_nop 0
	v_and_b32_e32 v117, v117, v209
	v_cvt_pk_bf16_f32 v208, v102, v103
	v_cvt_pk_bf16_f32 v209, v104, v105
	v_cvt_pk_bf16_f32 v210, v106, v107
	v_cvt_pk_bf16_f32 v211, v108, v109
	v_cvt_pk_bf16_f32 v212, v110, v111
	v_cvt_pk_bf16_f32 v213, v112, v113
	v_cvt_pk_bf16_f32 v214, v114, v115
	v_cvt_pk_bf16_f32 v215, v116, v117
	s_nop 1
	s_setprio 1
	s_waitcnt lgkmcnt(7)
	v_mfma_f32_32x32x16_bf16 v[54:69], v[248:251], v[208:211], v[54:69]
	ds_read_b128 v[248:251], v203 offset:17472
	v_add_f32_e32 v194, v194, v102
	v_add_f32_e32 v194, v103, v194
	s_waitcnt lgkmcnt(7)
	v_mfma_f32_32x32x16_bf16 v[54:69], v[222:225], v[212:215], v[54:69]
	ds_read_b128 v[222:225], v203 offset:17504
	v_add_f32_e32 v194, v104, v194
	v_add_f32_e32 v194, v105, v194
	s_waitcnt lgkmcnt(7)
	v_mfma_f32_32x32x16_bf16 v[38:53], v[216:219], v[208:211], v[38:53]
	ds_read_b128 v[216:219], v203 offset:22080
	v_add_f32_e32 v194, v106, v194
	v_add_f32_e32 v194, v107, v194
	s_waitcnt lgkmcnt(7)
	v_mfma_f32_32x32x16_bf16 v[38:53], v[228:231], v[212:215], v[38:53]
	ds_read_b128 v[228:231], v203 offset:22112
	v_add_f32_e32 v194, v108, v194
	v_add_f32_e32 v194, v109, v194
	s_waitcnt lgkmcnt(7)
	v_mfma_f32_32x32x16_bf16 v[22:37], v[232:235], v[208:211], v[22:37]
	ds_read_b128 v[232:235], v203 offset:26688
	v_add_f32_e32 v194, v110, v194
	v_add_f32_e32 v194, v111, v194
	s_waitcnt lgkmcnt(7)
	v_mfma_f32_32x32x16_bf16 v[22:37], v[236:239], v[212:215], v[22:37]
	ds_read_b128 v[236:239], v203 offset:26720
	v_add_f32_e32 v194, v112, v194
	v_add_f32_e32 v194, v113, v194
	s_waitcnt lgkmcnt(7)
; #define LAS __attribute__((address_space(3)))
; __device__ __forceinline__ unsigned pk2(float lo, float hi) { f32x2_t v = {lo, hi}; bf16x2_t b = __builtin_convertvector(v, bf16x2_t); return __builtin_bit_cast(unsigned, b); }
; __device__ __forceinline__ void dsa_unit32(const Args& a, LAS unsigned char* lds, const LAS unsigned long long* maskl, int b, int qb, int tid, int wave, int lane) {
;     ...
;     auto compute = [&](int buf, int kt) {
;         const unsigned long long mw = maskl[l31 * 32 + kt];
;         const LAS bf16* Ks = (const LAS bf16*)(lds + buf * STG); const LAS bf16* Vs = (const LAS bf16*)(lds + buf * STG + KBYTES);
;         f32x16 S2[2];
; #pragma unroll
;         for (int kh = 0; kh < 2; ++kh) {
; #pragma unroll
;             for (int i = 0; i < 16; ++i) S2[kh][i] = negB;
;             __builtin_amdgcn_s_setprio(1);
; #pragma unroll
;             for (int ks = 0; ks < 8; ++ks) S2[kh] = mfma32(*(const LAS bf16x8*)(Ks + (32 * kh + l31) * KS + 16 * ks + 8 * hi), qf[ks], S2[kh]);
;             __builtin_amdgcn_s_setprio(0);
;         }
; #pragma unroll
;         for (int kh = 0; kh < 2; ++kh) {
;             const unsigned mh = (unsigned)(mw >> (32 * kh + 4 * hi));
;             float p[16];
; #pragma unroll
;             for (int i = 0; i < 16; ++i) { const float e = __builtin_amdgcn_exp2f(S2[kh][i]);
;                 const int keep = __builtin_amdgcn_sbfe((int)mh, 8 * (i >> 2) + (i & 3), 1);
;                 p[i] = __builtin_bit_cast(float, __builtin_bit_cast(int, e) & keep); l += p[i]; }
;             u32x4 w0, w1;
;             w0.x = pk2(p[0], p[1]); w0.y = pk2(p[2], p[3]); w0.z = pk2(p[4], p[5]); w0.w = pk2(p[6], p[7]);
;             w1.x = pk2(p[8], p[9]); w1.y = pk2(p[10], p[11]); w1.z = pk2(p[12], p[13]); w1.w = pk2(p[14], p[15]);
;             const bf16x8 pa = __builtin_bit_cast(bf16x8, w0), pb = __builtin_bit_cast(bf16x8, w1);
;             __builtin_amdgcn_s_setprio(1);
; #pragma unroll
;             for (int ct = 0; ct < 4; ++ct) {
;                 const LAS bf16* vr = Vs + (32 * ct + l31) * VS + 4 * hi + 32 * kh;
;                 O[ct] = mfma32(cat8(*(const LAS u32x2*)(vr), *(const LAS u32x2*)(vr + 8)), pa, O[ct]);
;                 O[ct] = mfma32(cat8(*(const LAS u32x2*)(vr + 16), *(const LAS u32x2*)(vr + 24)), pb, O[ct]);
;             }
;             __builtin_amdgcn_s_setprio(0);
;         }
;     };
	v_mfma_f32_32x32x16_bf16 v[6:21], v[240:243], v[208:211], v[6:21]
	ds_read_b128 v[240:243], v203 offset:31296
	v_add_f32_e32 v194, v114, v194
	v_add_f32_e32 v194, v115, v194
	s_waitcnt lgkmcnt(7)
	v_mfma_f32_32x32x16_bf16 v[6:21], v[244:247], v[212:215], v[6:21]
	ds_read_b128 v[244:247], v203 offset:31328
	v_add_f32_e32 v194, v116, v194
	v_add_f32_e32 v194, v117, v194
	s_setprio 0
	v_lshrrev_b64 v[208:209], v184, v[220:221]
	v_exp_f32_e32 v86, v86
	v_bfe_i32 v209, v208, 0, 1
	v_exp_f32_e32 v87, v87
	v_bfe_i32 v210, v208, 1, 1
	v_and_b32_e32 v86, v86, v209
	v_exp_f32_e32 v88, v88
	v_bfe_i32 v211, v208, 2, 1
	v_and_b32_e32 v87, v87, v210
	v_exp_f32_e32 v89, v89
	v_bfe_i32 v209, v208, 3, 1
	v_and_b32_e32 v88, v88, v211
	v_exp_f32_e32 v90, v90
	v_bfe_i32 v210, v208, 8, 1
	v_and_b32_e32 v89, v89, v209
	v_exp_f32_e32 v91, v91
	v_bfe_i32 v211, v208, 9, 1
	v_and_b32_e32 v90, v90, v210
	v_exp_f32_e32 v92, v92
	v_bfe_i32 v209, v208, 10, 1
	v_and_b32_e32 v91, v91, v211
	v_exp_f32_e32 v93, v93
	v_bfe_i32 v210, v208, 11, 1
	v_and_b32_e32 v92, v92, v209
	v_exp_f32_e32 v94, v94
	v_bfe_i32 v211, v208, 16, 1
	v_and_b32_e32 v93, v93, v210
	v_exp_f32_e32 v95, v95
	v_bfe_i32 v209, v208, 17, 1
	v_and_b32_e32 v94, v94, v211
	v_exp_f32_e32 v96, v96
	v_bfe_i32 v210, v208, 18, 1
	v_and_b32_e32 v95, v95, v209
	v_exp_f32_e32 v97, v97
	v_bfe_i32 v211, v208, 19, 1
	v_and_b32_e32 v96, v96, v210
	v_exp_f32_e32 v98, v98
	v_bfe_i32 v209, v208, 24, 1
	v_and_b32_e32 v97, v97, v211
	v_exp_f32_e32 v99, v99
	v_bfe_i32 v210, v208, 25, 1
	v_and_b32_e32 v98, v98, v209
	v_exp_f32_e32 v100, v100
	v_bfe_i32 v211, v208, 26, 1
	v_and_b32_e32 v99, v99, v210
	v_exp_f32_e32 v101, v101
	v_bfe_i32 v209, v208, 27, 1
	v_and_b32_e32 v100, v100, v211
	s_nop 0
	v_and_b32_e32 v101, v101, v209
	v_cvt_pk_bf16_f32 v208, v86, v87
	v_cvt_pk_bf16_f32 v209, v88, v89
	v_cvt_pk_bf16_f32 v210, v90, v91
	v_cvt_pk_bf16_f32 v211, v92, v93
	v_cvt_pk_bf16_f32 v212, v94, v95
	v_cvt_pk_bf16_f32 v213, v96, v97
	v_cvt_pk_bf16_f32 v214, v98, v99
	v_cvt_pk_bf16_f32 v215, v100, v101
	s_nop 1
	s_setprio 1
	s_waitcnt lgkmcnt(7)
	v_mfma_f32_32x32x16_bf16 v[54:69], v[248:251], v[208:211], v[54:69]
	v_add_f32_e32 v194, v194, v86
	v_add_f32_e32 v194, v87, v194
	s_waitcnt lgkmcnt(6)
	v_mfma_f32_32x32x16_bf16 v[54:69], v[222:225], v[212:215], v[54:69]
	v_add_f32_e32 v194, v88, v194
	v_add_f32_e32 v194, v89, v194
	s_waitcnt lgkmcnt(5)
	v_mfma_f32_32x32x16_bf16 v[38:53], v[216:219], v[208:211], v[38:53]
	v_add_f32_e32 v194, v90, v194
	v_add_f32_e32 v194, v91, v194
	s_waitcnt lgkmcnt(4)
	v_mfma_f32_32x32x16_bf16 v[38:53], v[228:231], v[212:215], v[38:53]
	v_add_f32_e32 v194, v92, v194
	v_add_f32_e32 v194, v93, v194
	s_waitcnt lgkmcnt(3)
	v_mfma_f32_32x32x16_bf16 v[22:37], v[232:235], v[208:211], v[22:37]
	v_add_f32_e32 v194, v94, v194
	v_add_f32_e32 v194, v95, v194
	s_waitcnt lgkmcnt(2)
	v_mfma_f32_32x32x16_bf16 v[22:37], v[236:239], v[212:215], v[22:37]
	v_add_f32_e32 v194, v96, v194
	v_add_f32_e32 v194, v97, v194
	s_waitcnt lgkmcnt(1)
	v_mfma_f32_32x32x16_bf16 v[6:21], v[240:243], v[208:211], v[6:21]
	v_add_f32_e32 v194, v98, v194
	v_add_f32_e32 v194, v99, v194
	s_waitcnt lgkmcnt(0)
	v_mfma_f32_32x32x16_bf16 v[6:21], v[244:247], v[212:215], v[6:21]
	v_add_f32_e32 v194, v100, v194
	v_add_f32_e32 v194, v101, v194
	s_setprio 0
	s_branch .Ldsa_J0
.Ldsa_B0:
	v_add_u32_e32 v207, -8, v206
	ds_read_b64 v[220:221], v207
	v_add_u32_e32 v207, v202, v180
	ds_read_b128 v[216:219], v207 offset:0
	ds_read_b128 v[228:231], v207 offset:32
	ds_read_b128 v[232:235], v207 offset:64
	ds_read_b128 v[236:239], v207 offset:96
	ds_read_b128 v[240:243], v207 offset:128
	ds_read_b128 v[244:247], v207 offset:160
	ds_read_b128 v[248:251], v207 offset:192
	ds_read_b128 v[222:225], v207 offset:224
	s_setprio 1
	s_waitcnt lgkmcnt(7)
	v_mfma_f32_32x32x16_bf16 v[102:117], v[216:219], v[126:129], v[70:85]
	ds_read_b128 v[216:219], v207 offset:8704
	s_waitcnt lgkmcnt(7)
	v_mfma_f32_32x32x16_bf16 v[102:117], v[228:231], v[0:3], v[102:117]
	ds_read_b128 v[228:231], v207 offset:8736
	s_waitcnt lgkmcnt(7)
	v_mfma_f32_32x32x16_bf16 v[102:117], v[232:235], v[118:121], v[102:117]
	ds_read_b128 v[232:235], v207 offset:8768
	s_waitcnt lgkmcnt(7)
	v_mfma_f32_32x32x16_bf16 v[102:117], v[236:239], v[122:125], v[102:117]
	ds_read_b128 v[236:239], v207 offset:8800
	s_waitcnt lgkmcnt(7)
	v_mfma_f32_32x32x16_bf16 v[102:117], v[240:243], v[130:133], v[102:117]
	ds_read_b128 v[240:243], v207 offset:8832
	s_waitcnt lgkmcnt(7)
	v_mfma_f32_32x32x16_bf16 v[102:117], v[244:247], v[134:137], v[102:117]
	ds_read_b128 v[244:247], v207 offset:8864
	s_waitcnt lgkmcnt(7)
	v_mfma_f32_32x32x16_bf16 v[102:117], v[248:251], v[138:141], v[102:117]
	ds_read_b128 v[248:251], v207 offset:8896
	s_waitcnt lgkmcnt(7)
; #define LAS __attribute__((address_space(3)))
; __device__ __forceinline__ unsigned pk2(float lo, float hi) { f32x2_t v = {lo, hi}; bf16x2_t b = __builtin_convertvector(v, bf16x2_t); return __builtin_bit_cast(unsigned, b); }
; __device__ __forceinline__ void dsa_unit32(const Args& a, LAS unsigned char* lds, const LAS unsigned long long* maskl, int b, int qb, int tid, int wave, int lane) {
;     ...
;     auto compute = [&](int buf, int kt) {
;         const unsigned long long mw = maskl[l31 * 32 + kt];
;         const LAS bf16* Ks = (const LAS bf16*)(lds + buf * STG); const LAS bf16* Vs = (const LAS bf16*)(lds + buf * STG + KBYTES);
;         f32x16 S2[2];
; #pragma unroll
;         for (int kh = 0; kh < 2; ++kh) {
; #pragma unroll
;             for (int i = 0; i < 16; ++i) S2[kh][i] = negB;
;             __builtin_amdgcn_s_setprio(1);
; #pragma unroll
;             for (int ks = 0; ks < 8; ++ks) S2[kh] = mfma32(*(const LAS bf16x8*)(Ks + (32 * kh + l31) * KS + 16 * ks + 8 * hi), qf[ks], S2[kh]);
;             __builtin_amdgcn_s_setprio(0);
;         }
; #pragma unroll
;         for (int kh = 0; kh < 2; ++kh) {
;             const unsigned mh = (unsigned)(mw >> (32 * kh + 4 * hi));
;             float p[16];
; #pragma unroll
;             for (int i = 0; i < 16; ++i) { const float e = __builtin_amdgcn_exp2f(S2[kh][i]);
;                 const int keep = __builtin_amdgcn_sbfe((int)mh, 8 * (i >> 2) + (i & 3), 1);
;                 p[i] = __builtin_bit_cast(float, __builtin_bit_cast(int, e) & keep); l += p[i]; }
;             u32x4 w0, w1;
;             w0.x = pk2(p[0], p[1]); w0.y = pk2(p[2], p[3]); w0.z = pk2(p[4], p[5]); w0.w = pk2(p[6], p[7]);
;             w1.x = pk2(p[8], p[9]); w1.y = pk2(p[10], p[11]); w1.z = pk2(p[12], p[13]); w1.w = pk2(p[14], p[15]);
;             const bf16x8 pa = __builtin_bit_cast(bf16x8, w0), pb = __builtin_bit_cast(bf16x8, w1);
;             __builtin_amdgcn_s_setprio(1);
; #pragma unroll
;             for (int ct = 0; ct < 4; ++ct) {
;                 const LAS bf16* vr = Vs + (32 * ct + l31) * VS + 4 * hi + 32 * kh;
;                 O[ct] = mfma32(cat8(*(const LAS u32x2*)(vr), *(const LAS u32x2*)(vr + 8)), pa, O[ct]);
;                 O[ct] = mfma32(cat8(*(const LAS u32x2*)(vr + 16), *(const LAS u32x2*)(vr + 24)), pb, O[ct]);
;             }
;             __builtin_amdgcn_s_setprio(0);
;         }
;     };
	v_mfma_f32_32x32x16_bf16 v[102:117], v[222:225], v[142:145], v[102:117]
	ds_read_b128 v[222:225], v207 offset:8928
	s_setprio 0
	s_nop 7
	s_nop 3
	v_lshrrev_b64 v[208:209], v182, v[220:221]
	v_exp_f32_e32 v102, v102
	v_bfe_i32 v209, v208, 0, 1
	v_exp_f32_e32 v103, v103
	v_bfe_i32 v210, v208, 1, 1
	v_and_b32_e32 v102, v102, v209
	v_exp_f32_e32 v104, v104
	v_bfe_i32 v211, v208, 2, 1
	v_and_b32_e32 v103, v103, v210
	v_exp_f32_e32 v105, v105
	v_bfe_i32 v209, v208, 3, 1
	v_and_b32_e32 v104, v104, v211
	v_exp_f32_e32 v106, v106
	v_bfe_i32 v210, v208, 8, 1
	v_and_b32_e32 v105, v105, v209
	v_exp_f32_e32 v107, v107
	v_bfe_i32 v211, v208, 9, 1
	v_and_b32_e32 v106, v106, v210
	v_exp_f32_e32 v108, v108
	v_bfe_i32 v209, v208, 10, 1
	v_and_b32_e32 v107, v107, v211
	v_exp_f32_e32 v109, v109
	v_bfe_i32 v210, v208, 11, 1
	v_and_b32_e32 v108, v108, v209
	v_exp_f32_e32 v110, v110
	v_bfe_i32 v211, v208, 16, 1
	v_and_b32_e32 v109, v109, v210
	v_exp_f32_e32 v111, v111
	v_bfe_i32 v209, v208, 17, 1
	v_and_b32_e32 v110, v110, v211
	v_exp_f32_e32 v112, v112
	v_bfe_i32 v210, v208, 18, 1
	v_and_b32_e32 v111, v111, v209
	v_exp_f32_e32 v113, v113
	v_bfe_i32 v211, v208, 19, 1
	v_and_b32_e32 v112, v112, v210
	v_exp_f32_e32 v114, v114
	v_bfe_i32 v209, v208, 24, 1
	v_and_b32_e32 v113, v113, v211
	v_exp_f32_e32 v115, v115
	v_bfe_i32 v210, v208, 25, 1
	v_and_b32_e32 v114, v114, v209
	v_exp_f32_e32 v116, v116
	v_bfe_i32 v211, v208, 26, 1
	v_and_b32_e32 v115, v115, v210
	v_exp_f32_e32 v117, v117
	v_bfe_i32 v209, v208, 27, 1
	v_and_b32_e32 v116, v116, v211
	s_nop 0
	v_and_b32_e32 v117, v117, v209
	v_cvt_pk_bf16_f32 v208, v102, v103
	v_cvt_pk_bf16_f32 v209, v104, v105
	v_cvt_pk_bf16_f32 v210, v106, v107
	v_cvt_pk_bf16_f32 v211, v108, v109
	v_cvt_pk_bf16_f32 v212, v110, v111
	v_cvt_pk_bf16_f32 v213, v112, v113
	v_cvt_pk_bf16_f32 v214, v114, v115
	v_cvt_pk_bf16_f32 v215, v116, v117
	s_setprio 1
	s_waitcnt lgkmcnt(7)
	v_mfma_f32_32x32x16_bf16 v[86:101], v[216:219], v[126:129], v[70:85]
	ds_read_b128 v[216:219], v203 offset:17408
	s_waitcnt lgkmcnt(7)
	v_mfma_f32_32x32x16_bf16 v[86:101], v[228:231], v[0:3], v[86:101]
	ds_read_b128 v[228:231], v203 offset:17440
	s_waitcnt lgkmcnt(7)
	v_mfma_f32_32x32x16_bf16 v[86:101], v[232:235], v[118:121], v[86:101]
	ds_read_b128 v[232:235], v203 offset:22016
	s_waitcnt lgkmcnt(7)
	v_mfma_f32_32x32x16_bf16 v[86:101], v[236:239], v[122:125], v[86:101]
	ds_read_b128 v[236:239], v203 offset:22048
	s_waitcnt lgkmcnt(7)
	v_mfma_f32_32x32x16_bf16 v[86:101], v[240:243], v[130:133], v[86:101]
	ds_read_b128 v[240:243], v203 offset:26624
	s_waitcnt lgkmcnt(7)
	v_mfma_f32_32x32x16_bf16 v[86:101], v[244:247], v[134:137], v[86:101]
	ds_read_b128 v[244:247], v203 offset:26656
	s_waitcnt lgkmcnt(7)
	v_mfma_f32_32x32x16_bf16 v[86:101], v[248:251], v[138:141], v[86:101]
	ds_read_b128 v[248:251], v203 offset:31232
	s_waitcnt lgkmcnt(7)
; #define LAS __attribute__((address_space(3)))
; __device__ __forceinline__ void dsa_unit32(const Args& a, LAS unsigned char* lds, const LAS unsigned long long* maskl, int b, int qb, int tid, int wave, int lane) {
;     ...
;     auto compute = [&](int buf, int kt) {
;         const unsigned long long mw = maskl[l31 * 32 + kt];
;         const LAS bf16* Ks = (const LAS bf16*)(lds + buf * STG); const LAS bf16* Vs = (const LAS bf16*)(lds + buf * STG + KBYTES);
;         f32x16 S2[2];
; #pragma unroll
;         for (int kh = 0; kh < 2; ++kh) {
; #pragma unroll
;             for (int i = 0; i < 16; ++i) S2[kh][i] = negB;
;             __builtin_amdgcn_s_setprio(1);
; #pragma unroll
;             for (int ks = 0; ks < 8; ++ks) S2[kh] = mfma32(*(const LAS bf16x8*)(Ks + (32 * kh + l31) * KS + 16 * ks + 8 * hi), qf[ks], S2[kh]);
;             __builtin_amdgcn_s_setprio(0);
;         }
; #pragma unroll
;         for (int kh = 0; kh < 2; ++kh) {
;             const unsigned mh = (unsigned)(mw >> (32 * kh + 4 * hi));
;             float p[16];
; #pragma unroll
;             for (int i = 0; i < 16; ++i) { const float e = __builtin_amdgcn_exp2f(S2[kh][i]);
;                 const int keep = __builtin_amdgcn_sbfe((int)mh, 8 * (i >> 2) + (i & 3), 1);
;                 p[i] = __builtin_bit_cast(float, __builtin_bit_cast(int, e) & keep); l += p[i]; }
;             u32x4 w0, w1;
;             w0.x = pk2(p[0], p[1]); w0.y = pk2(p[2], p[3]); w0.z = pk2(p[4], p[5]); w0.w = pk2(p[6], p[7]);
;             w1.x = pk2(p[8], p[9]); w1.y = pk2(p[10], p[11]); w1.z = pk2(p[12], p[13]); w1.w = pk2(p[14], p[15]);
;             const bf16x8 pa = __builtin_bit_cast(bf16x8, w0), pb = __builtin_bit_cast(bf16x8, w1);
;             __builtin_amdgcn_s_setprio(1);
; #pragma unroll
;             for (int ct = 0; ct < 4; ++ct) {
;                 const LAS bf16* vr = Vs + (32 * ct + l31) * VS + 4 * hi + 32 * kh;
;                 O[ct] = mfma32(cat8(*(const LAS u32x2*)(vr), *(const LAS u32x2*)(vr + 8)), pa, O[ct]);
;                 O[ct] = mfma32(cat8(*(const LAS u32x2*)(vr + 16), *(const LAS u32x2*)(vr + 24)), pb, O[ct]);
;             }
;             __builtin_amdgcn_s_setprio(0);
;         }
;     };
;     ...
;         if (kt + 2 < nkt) DSA_GLOAD(kt + 2, rk0, rv0);
;         compute(0, kt);
;         if (kt + 1 < nkt) DSA_LSTORE(1, rk1, rv1);
	v_mfma_f32_32x32x16_bf16 v[86:101], v[222:225], v[142:145], v[86:101]
	ds_read_b128 v[222:225], v203 offset:31264
	s_setprio 0
	v_add_f32_e32 v194, v194, v102
	v_add_f32_e32 v194, v103, v194
	v_add_f32_e32 v194, v104, v194
	v_add_f32_e32 v194, v105, v194
	v_add_f32_e32 v194, v106, v194
	v_add_f32_e32 v194, v107, v194
	v_add_f32_e32 v194, v108, v194
	v_add_f32_e32 v194, v109, v194
	v_add_f32_e32 v194, v110, v194
	v_add_f32_e32 v194, v111, v194
	v_add_f32_e32 v194, v112, v194
	v_add_f32_e32 v194, v113, v194
	v_add_f32_e32 v194, v114, v194
	v_add_f32_e32 v194, v115, v194
	v_add_f32_e32 v194, v116, v194
	v_add_f32_e32 v194, v117, v194
	v_lshrrev_b64 v[110:111], v184, v[220:221]
	v_exp_f32_e32 v86, v86
	v_bfe_i32 v111, v110, 0, 1
	v_exp_f32_e32 v87, v87
	v_bfe_i32 v112, v110, 1, 1
	v_and_b32_e32 v86, v86, v111
	v_exp_f32_e32 v88, v88
	v_bfe_i32 v113, v110, 2, 1
	v_and_b32_e32 v87, v87, v112
	v_exp_f32_e32 v89, v89
	v_bfe_i32 v111, v110, 3, 1
	v_and_b32_e32 v88, v88, v113
	v_exp_f32_e32 v90, v90
	v_bfe_i32 v112, v110, 8, 1
	v_and_b32_e32 v89, v89, v111
	v_exp_f32_e32 v91, v91
	v_bfe_i32 v113, v110, 9, 1
	v_and_b32_e32 v90, v90, v112
	v_exp_f32_e32 v92, v92
	v_bfe_i32 v111, v110, 10, 1
	v_and_b32_e32 v91, v91, v113
	v_exp_f32_e32 v93, v93
	v_bfe_i32 v112, v110, 11, 1
	v_and_b32_e32 v92, v92, v111
	v_exp_f32_e32 v94, v94
	v_bfe_i32 v113, v110, 16, 1
	v_and_b32_e32 v93, v93, v112
	v_exp_f32_e32 v95, v95
	v_bfe_i32 v111, v110, 17, 1
	v_and_b32_e32 v94, v94, v113
	v_exp_f32_e32 v96, v96
	v_bfe_i32 v112, v110, 18, 1
	v_and_b32_e32 v95, v95, v111
	v_exp_f32_e32 v97, v97
	v_bfe_i32 v113, v110, 19, 1
	v_and_b32_e32 v96, v96, v112
	v_exp_f32_e32 v98, v98
	v_bfe_i32 v111, v110, 24, 1
	v_and_b32_e32 v97, v97, v113
	v_exp_f32_e32 v99, v99
	v_bfe_i32 v112, v110, 25, 1
	v_and_b32_e32 v98, v98, v111
	v_exp_f32_e32 v100, v100
	v_bfe_i32 v113, v110, 26, 1
	v_and_b32_e32 v99, v99, v112
	v_exp_f32_e32 v101, v101
	v_bfe_i32 v111, v110, 27, 1
	v_and_b32_e32 v100, v100, v113
	s_nop 0
	v_and_b32_e32 v101, v101, v111
	v_cvt_pk_bf16_f32 v102, v86, v87
	v_cvt_pk_bf16_f32 v103, v88, v89
	v_cvt_pk_bf16_f32 v104, v90, v91
	v_cvt_pk_bf16_f32 v105, v92, v93
	v_cvt_pk_bf16_f32 v106, v94, v95
	v_cvt_pk_bf16_f32 v107, v96, v97
	v_cvt_pk_bf16_f32 v108, v98, v99
	v_cvt_pk_bf16_f32 v109, v100, v101
	s_nop 1
	s_setprio 1
	s_waitcnt lgkmcnt(7)
	v_mfma_f32_32x32x16_bf16 v[54:69], v[216:219], v[208:211], v[54:69]
	ds_read_b128 v[216:219], v203 offset:17472
	s_waitcnt lgkmcnt(7)
	v_mfma_f32_32x32x16_bf16 v[54:69], v[228:231], v[212:215], v[54:69]
	ds_read_b128 v[228:231], v203 offset:17504
	s_waitcnt lgkmcnt(7)
	v_mfma_f32_32x32x16_bf16 v[38:53], v[232:235], v[208:211], v[38:53]
	ds_read_b128 v[232:235], v203 offset:22080
	s_waitcnt lgkmcnt(7)
	v_mfma_f32_32x32x16_bf16 v[38:53], v[236:239], v[212:215], v[38:53]
	ds_read_b128 v[236:239], v203 offset:22112
	s_waitcnt lgkmcnt(7)
	v_mfma_f32_32x32x16_bf16 v[22:37], v[240:243], v[208:211], v[22:37]
	ds_read_b128 v[240:243], v203 offset:26688
	s_waitcnt lgkmcnt(7)
	v_mfma_f32_32x32x16_bf16 v[22:37], v[244:247], v[212:215], v[22:37]
	ds_read_b128 v[244:247], v203 offset:26720
	s_waitcnt lgkmcnt(7)
	v_mfma_f32_32x32x16_bf16 v[6:21], v[248:251], v[208:211], v[6:21]
	ds_read_b128 v[248:251], v203 offset:31296
	s_waitcnt lgkmcnt(7)
	v_mfma_f32_32x32x16_bf16 v[6:21], v[222:225], v[212:215], v[6:21]
	ds_read_b128 v[222:225], v203 offset:31328
	s_waitcnt lgkmcnt(7)
	v_mfma_f32_32x32x16_bf16 v[54:69], v[216:219], v[102:105], v[54:69]
	v_add_f32_e32 v194, v194, v86
	v_add_f32_e32 v194, v87, v194
	s_waitcnt lgkmcnt(6)
	v_mfma_f32_32x32x16_bf16 v[54:69], v[228:231], v[106:109], v[54:69]
	v_add_f32_e32 v194, v88, v194
	v_add_f32_e32 v194, v89, v194
	s_waitcnt lgkmcnt(5)
	v_mfma_f32_32x32x16_bf16 v[38:53], v[232:235], v[102:105], v[38:53]
	v_add_f32_e32 v194, v90, v194
	v_add_f32_e32 v194, v91, v194
	s_waitcnt lgkmcnt(4)
	v_mfma_f32_32x32x16_bf16 v[38:53], v[236:239], v[106:109], v[38:53]
	v_add_f32_e32 v194, v92, v194
	v_add_f32_e32 v194, v93, v194
	s_waitcnt lgkmcnt(3)
	v_mfma_f32_32x32x16_bf16 v[22:37], v[240:243], v[102:105], v[22:37]
	v_add_f32_e32 v194, v94, v194
	v_add_f32_e32 v194, v95, v194
	s_waitcnt lgkmcnt(2)
	v_mfma_f32_32x32x16_bf16 v[22:37], v[244:247], v[106:109], v[22:37]
	v_add_f32_e32 v194, v96, v194
	v_add_f32_e32 v194, v97, v194
	s_waitcnt lgkmcnt(1)
	v_mfma_f32_32x32x16_bf16 v[6:21], v[248:251], v[102:105], v[6:21]
	v_add_f32_e32 v194, v98, v194
	v_add_f32_e32 v194, v99, v194
	s_waitcnt lgkmcnt(0)
	v_mfma_f32_32x32x16_bf16 v[6:21], v[222:225], v[106:109], v[6:21]
	v_add_f32_e32 v194, v100, v194
	v_add_f32_e32 v194, v101, v194
	s_setprio 0
.Ldsa_J0:
	s_add_i32 s7, s5, -2
	s_cmp_lt_u32 s7, s4
	s_cselect_b64 s[2:3], -1, 0
	s_cmp_ge_u32 s7, s4
	s_cbranch_scc1 .LBB0_1306
	s_mov_b32 s7, 0xd400
	v_add3_u32 v208, v195, v197, s7
	s_waitcnt vmcnt(3)
	ds_write_b128 v196, v[162:165] offset:36864
	s_waitcnt vmcnt(1)
	ds_write2_b64 v208, v[170:171], v[172:173] offset1:2
	ds_write_b128 v199, v[166:169] offset:36864
	v_add3_u32 v208, v195, v200, s7
	s_waitcnt vmcnt(0)
	ds_write2_b64 v208, v[174:175], v[176:177] offset1:2

; #define LAS __attribute__((address_space(3)))
; __device__ __forceinline__ unsigned pk2(float lo, float hi) { f32x2_t v = {lo, hi}; bf16x2_t b = __builtin_convertvector(v, bf16x2_t); return __builtin_bit_cast(unsigned, b); }
; __device__ __forceinline__ void dsa_unit32(const Args& a, LAS unsigned char* lds, const LAS unsigned long long* maskl, int b, int qb, int tid, int wave, int lane) {
;     ...
;     auto compute = [&](int buf, int kt) {
;         const unsigned long long mw = maskl[l31 * 32 + kt];
;         const LAS bf16* Ks = (const LAS bf16*)(lds + buf * STG); const LAS bf16* Vs = (const LAS bf16*)(lds + buf * STG + KBYTES);
;         f32x16 S2[2];
; #pragma unroll
;         for (int kh = 0; kh < 2; ++kh) {
; #pragma unroll
;             for (int i = 0; i < 16; ++i) S2[kh][i] = negB;
;             __builtin_amdgcn_s_setprio(1);
; #pragma unroll
;             for (int ks = 0; ks < 8; ++ks) S2[kh] = mfma32(*(const LAS bf16x8*)(Ks + (32 * kh + l31) * KS + 16 * ks + 8 * hi), qf[ks], S2[kh]);
;             __builtin_amdgcn_s_setprio(0);
;         }
; #pragma unroll
;         for (int kh = 0; kh < 2; ++kh) {
;             const unsigned mh = (unsigned)(mw >> (32 * kh + 4 * hi));
;             float p[16];
; #pragma unroll
;             for (int i = 0; i < 16; ++i) { const float e = __builtin_amdgcn_exp2f(S2[kh][i]);
;                 const int keep = __builtin_amdgcn_sbfe((int)mh, 8 * (i >> 2) + (i & 3), 1);
;                 p[i] = __builtin_bit_cast(float, __builtin_bit_cast(int, e) & keep); l += p[i]; }
;             u32x4 w0, w1;
;             w0.x = pk2(p[0], p[1]); w0.y = pk2(p[2], p[3]); w0.z = pk2(p[4], p[5]); w0.w = pk2(p[6], p[7]);
;             w1.x = pk2(p[8], p[9]); w1.y = pk2(p[10], p[11]); w1.z = pk2(p[12], p[13]); w1.w = pk2(p[14], p[15]);
;             const bf16x8 pa = __builtin_bit_cast(bf16x8, w0), pb = __builtin_bit_cast(bf16x8, w1);
;             __builtin_amdgcn_s_setprio(1);
; #pragma unroll
;             for (int ct = 0; ct < 4; ++ct) {
;                 const LAS bf16* vr = Vs + (32 * ct + l31) * VS + 4 * hi + 32 * kh;
;                 O[ct] = mfma32(cat8(*(const LAS u32x2*)(vr), *(const LAS u32x2*)(vr + 8)), pa, O[ct]);
;                 O[ct] = mfma32(cat8(*(const LAS u32x2*)(vr + 16), *(const LAS u32x2*)(vr + 24)), pb, O[ct]);
;             }
;             __builtin_amdgcn_s_setprio(0);
;         }
;     };
.LBB0_1309:
	s_cmp_lt_u32 s17, 4
	s_cbranch_scc0 .Ldsa_B1
	ds_read_b64 v[220:221], v206
	v_add_u32_e32 v207, v202, v180
	ds_read_b128 v[216:219], v207 offset:36864
	ds_read_b128 v[228:231], v207 offset:36896
	ds_read_b128 v[232:235], v207 offset:36928
	ds_read_b128 v[236:239], v207 offset:36960
	ds_read_b128 v[240:243], v207 offset:36992
	ds_read_b128 v[244:247], v207 offset:37024
	ds_read_b128 v[248:251], v207 offset:37056
	ds_read_b128 v[222:225], v207 offset:37088
	ds_read_b128 v[208:211], v207 offset:45568
	ds_read_b128 v[212:215], v207 offset:45600
	s_setprio 1
	s_waitcnt lgkmcnt(9)
	v_mfma_f32_32x32x16_bf16 v[102:117], v[216:219], v[126:129], v[70:85]
	ds_read_b128 v[216:219], v207 offset:45632
	s_waitcnt lgkmcnt(9)
	v_mfma_f32_32x32x16_bf16 v[102:117], v[228:231], v[0:3], v[102:117]
	ds_read_b128 v[228:231], v207 offset:45664
	s_waitcnt lgkmcnt(9)
	v_mfma_f32_32x32x16_bf16 v[102:117], v[232:235], v[118:121], v[102:117]
	ds_read_b128 v[232:235], v207 offset:45696
	s_waitcnt lgkmcnt(9)
	v_mfma_f32_32x32x16_bf16 v[102:117], v[236:239], v[122:125], v[102:117]
	ds_read_b128 v[236:239], v207 offset:45728
	s_waitcnt lgkmcnt(9)
	v_mfma_f32_32x32x16_bf16 v[102:117], v[240:243], v[130:133], v[102:117]
	ds_read_b128 v[240:243], v207 offset:45760
	s_waitcnt lgkmcnt(9)
	v_mfma_f32_32x32x16_bf16 v[102:117], v[244:247], v[134:137], v[102:117]
	ds_read_b128 v[244:247], v207 offset:45792
	s_waitcnt lgkmcnt(9)
	v_mfma_f32_32x32x16_bf16 v[102:117], v[248:251], v[138:141], v[102:117]
	s_waitcnt lgkmcnt(8)
	v_mfma_f32_32x32x16_bf16 v[102:117], v[222:225], v[142:145], v[102:117]
	s_waitcnt lgkmcnt(7)
	v_mfma_f32_32x32x16_bf16 v[86:101], v[208:211], v[126:129], v[70:85]
	s_waitcnt lgkmcnt(6)
	v_mfma_f32_32x32x16_bf16 v[86:101], v[212:215], v[0:3], v[86:101]
	s_waitcnt lgkmcnt(5)
	v_mfma_f32_32x32x16_bf16 v[86:101], v[216:219], v[118:121], v[86:101]
	ds_read_b128 v[248:251], v204 offset:0
	ds_read_b128 v[222:225], v204 offset:32
	ds_read_b128 v[216:219], v204 offset:4608
	s_waitcnt lgkmcnt(7)
	v_mfma_f32_32x32x16_bf16 v[86:101], v[228:231], v[122:125], v[86:101]
	ds_read_b128 v[228:231], v204 offset:4640
	s_waitcnt lgkmcnt(7)
	v_mfma_f32_32x32x16_bf16 v[86:101], v[232:235], v[130:133], v[86:101]
	ds_read_b128 v[232:235], v204 offset:9216
	s_waitcnt lgkmcnt(7)
	v_mfma_f32_32x32x16_bf16 v[86:101], v[236:239], v[134:137], v[86:101]
	ds_read_b128 v[236:239], v204 offset:9248
	s_waitcnt lgkmcnt(7)
	v_mfma_f32_32x32x16_bf16 v[86:101], v[240:243], v[138:141], v[86:101]
	ds_read_b128 v[240:243], v204 offset:13824
	s_waitcnt lgkmcnt(7)
	v_mfma_f32_32x32x16_bf16 v[86:101], v[244:247], v[142:145], v[86:101]
	ds_read_b128 v[244:247], v204 offset:13856
	s_setprio 0
	v_lshrrev_b64 v[208:209], v182, v[220:221]
	v_exp_f32_e32 v102, v102
	v_bfe_i32 v209, v208, 0, 1
	v_exp_f32_e32 v103, v103
	v_bfe_i32 v210, v208, 1, 1
	v_and_b32_e32 v102, v102, v209
	v_exp_f32_e32 v104, v104
	v_bfe_i32 v211, v208, 2, 1
	v_and_b32_e32 v103, v103, v210
	v_exp_f32_e32 v105, v105
	v_bfe_i32 v209, v208, 3, 1
	v_and_b32_e32 v104, v104, v211
	v_exp_f32_e32 v106, v106
	v_bfe_i32 v210, v208, 8, 1
	v_and_b32_e32 v105, v105, v209
	v_exp_f32_e32 v107, v107
	v_bfe_i32 v211, v208, 9, 1
	v_and_b32_e32 v106, v106, v210
	v_exp_f32_e32 v108, v108
	v_bfe_i32 v209, v208, 10, 1
	v_and_b32_e32 v107, v107, v211
	v_exp_f32_e32 v109, v109
	v_bfe_i32 v210, v208, 11, 1
	v_and_b32_e32 v108, v108, v209
	v_exp_f32_e32 v110, v110
	v_bfe_i32 v211, v208, 16, 1
	v_and_b32_e32 v109, v109, v210
	v_exp_f32_e32 v111, v111
	v_bfe_i32 v209, v208, 17, 1
	v_and_b32_e32 v110, v110, v211
	v_exp_f32_e32 v112, v112
	v_bfe_i32 v210, v208, 18, 1
	v_and_b32_e32 v111, v111, v209
	v_exp_f32_e32 v113, v113
	v_bfe_i32 v211, v208, 19, 1
	v_and_b32_e32 v112, v112, v210
	v_exp_f32_e32 v114, v114
	v_bfe_i32 v209, v208, 24, 1
	v_and_b32_e32 v113, v113, v211
	v_exp_f32_e32 v115, v115
	v_bfe_i32 v210, v208, 25, 1
	v_and_b32_e32 v114, v114, v209
	v_exp_f32_e32 v116, v116
	v_bfe_i32 v211, v208, 26, 1
	v_and_b32_e32 v115, v115, v210
	v_exp_f32_e32 v117, v117
	v_bfe_i32 v209, v208, 27, 1
	v_and_b32_e32 v116, v116, v211
	s_nop 0
	v_and_b32_e32 v117, v117, v209
	v_cvt_pk_bf16_f32 v208, v102, v103
	v_cvt_pk_bf16_f32 v209, v104, v105
	v_cvt_pk_bf16_f32 v210, v106, v107
	v_cvt_pk_bf16_f32 v211, v108, v109
	v_cvt_pk_bf16_f32 v212, v110, v111
	v_cvt_pk_bf16_f32 v213, v112, v113
	v_cvt_pk_bf16_f32 v214, v114, v115
	v_cvt_pk_bf16_f32 v215, v116, v117
	s_nop 1
	s_setprio 1
	s_waitcnt lgkmcnt(7)
	v_mfma_f32_32x32x16_bf16 v[54:69], v[248:251], v[208:211], v[54:69]
	ds_read_b128 v[248:251], v204 offset:64
	v_add_f32_e32 v194, v194, v102
	v_add_f32_e32 v194, v103, v194
	s_waitcnt lgkmcnt(7)
	v_mfma_f32_32x32x16_bf16 v[54:69], v[222:225], v[212:215], v[54:69]
	ds_read_b128 v[222:225], v204 offset:96
	v_add_f32_e32 v194, v104, v194
	v_add_f32_e32 v194, v105, v194
	s_waitcnt lgkmcnt(7)
	v_mfma_f32_32x32x16_bf16 v[38:53], v[216:219], v[208:211], v[38:53]
	ds_read_b128 v[216:219], v204 offset:4672
	v_add_f32_e32 v194, v106, v194
	v_add_f32_e32 v194, v107, v194
	s_waitcnt lgkmcnt(7)
	v_mfma_f32_32x32x16_bf16 v[38:53], v[228:231], v[212:215], v[38:53]
	ds_read_b128 v[228:231], v204 offset:4704
	v_add_f32_e32 v194, v108, v194
	v_add_f32_e32 v194, v109, v194
	s_waitcnt lgkmcnt(7)
	v_mfma_f32_32x32x16_bf16 v[22:37], v[232:235], v[208:211], v[22:37]
	ds_read_b128 v[232:235], v204 offset:9280
	v_add_f32_e32 v194, v110, v194
	v_add_f32_e32 v194, v111, v194
	s_waitcnt lgkmcnt(7)
	v_mfma_f32_32x32x16_bf16 v[22:37], v[236:239], v[212:215], v[22:37]
	ds_read_b128 v[236:239], v204 offset:9312
	v_add_f32_e32 v194, v112, v194
	v_add_f32_e32 v194, v113, v194
	s_waitcnt lgkmcnt(7)
; #define LAS __attribute__((address_space(3)))
; __device__ __forceinline__ unsigned pk2(float lo, float hi) { f32x2_t v = {lo, hi}; bf16x2_t b = __builtin_convertvector(v, bf16x2_t); return __builtin_bit_cast(unsigned, b); }
; __device__ __forceinline__ void dsa_unit32(const Args& a, LAS unsigned char* lds, const LAS unsigned long long* maskl, int b, int qb, int tid, int wave, int lane) {
;     ...
;     auto compute = [&](int buf, int kt) {
;         const unsigned long long mw = maskl[l31 * 32 + kt];
;         const LAS bf16* Ks = (const LAS bf16*)(lds + buf * STG); const LAS bf16* Vs = (const LAS bf16*)(lds + buf * STG + KBYTES);
;         f32x16 S2[2];
; #pragma unroll
;         for (int kh = 0; kh < 2; ++kh) {
; #pragma unroll
;             for (int i = 0; i < 16; ++i) S2[kh][i] = negB;
;             __builtin_amdgcn_s_setprio(1);
; #pragma unroll
;             for (int ks = 0; ks < 8; ++ks) S2[kh] = mfma32(*(const LAS bf16x8*)(Ks + (32 * kh + l31) * KS + 16 * ks + 8 * hi), qf[ks], S2[kh]);
;             __builtin_amdgcn_s_setprio(0);
;         }
; #pragma unroll
;         for (int kh = 0; kh < 2; ++kh) {
;             const unsigned mh = (unsigned)(mw >> (32 * kh + 4 * hi));
;             float p[16];
; #pragma unroll
;             for (int i = 0; i < 16; ++i) { const float e = __builtin_amdgcn_exp2f(S2[kh][i]);
;                 const int keep = __builtin_amdgcn_sbfe((int)mh, 8 * (i >> 2) + (i & 3), 1);
;                 p[i] = __builtin_bit_cast(float, __builtin_bit_cast(int, e) & keep); l += p[i]; }
;             u32x4 w0, w1;
;             w0.x = pk2(p[0], p[1]); w0.y = pk2(p[2], p[3]); w0.z = pk2(p[4], p[5]); w0.w = pk2(p[6], p[7]);
;             w1.x = pk2(p[8], p[9]); w1.y = pk2(p[10], p[11]); w1.z = pk2(p[12], p[13]); w1.w = pk2(p[14], p[15]);
;             const bf16x8 pa = __builtin_bit_cast(bf16x8, w0), pb = __builtin_bit_cast(bf16x8, w1);
;             __builtin_amdgcn_s_setprio(1);
; #pragma unroll
;             for (int ct = 0; ct < 4; ++ct) {
;                 const LAS bf16* vr = Vs + (32 * ct + l31) * VS + 4 * hi + 32 * kh;
;                 O[ct] = mfma32(cat8(*(const LAS u32x2*)(vr), *(const LAS u32x2*)(vr + 8)), pa, O[ct]);
;                 O[ct] = mfma32(cat8(*(const LAS u32x2*)(vr + 16), *(const LAS u32x2*)(vr + 24)), pb, O[ct]);
;             }
;             __builtin_amdgcn_s_setprio(0);
;         }
;     };
	v_mfma_f32_32x32x16_bf16 v[6:21], v[240:243], v[208:211], v[6:21]
	ds_read_b128 v[240:243], v204 offset:13888
	v_add_f32_e32 v194, v114, v194
	v_add_f32_e32 v194, v115, v194
	s_waitcnt lgkmcnt(7)
	v_mfma_f32_32x32x16_bf16 v[6:21], v[244:247], v[212:215], v[6:21]
	ds_read_b128 v[244:247], v204 offset:13920
	v_add_f32_e32 v194, v116, v194
	v_add_f32_e32 v194, v117, v194
	s_setprio 0
	v_lshrrev_b64 v[208:209], v184, v[220:221]
	v_exp_f32_e32 v86, v86
	v_bfe_i32 v209, v208, 0, 1
	v_exp_f32_e32 v87, v87
	v_bfe_i32 v210, v208, 1, 1
	v_and_b32_e32 v86, v86, v209
	v_exp_f32_e32 v88, v88
	v_bfe_i32 v211, v208, 2, 1
	v_and_b32_e32 v87, v87, v210
	v_exp_f32_e32 v89, v89
	v_bfe_i32 v209, v208, 3, 1
	v_and_b32_e32 v88, v88, v211
	v_exp_f32_e32 v90, v90
	v_bfe_i32 v210, v208, 8, 1
	v_and_b32_e32 v89, v89, v209
	v_exp_f32_e32 v91, v91
	v_bfe_i32 v211, v208, 9, 1
	v_and_b32_e32 v90, v90, v210
	v_exp_f32_e32 v92, v92
	v_bfe_i32 v209, v208, 10, 1
	v_and_b32_e32 v91, v91, v211
	v_exp_f32_e32 v93, v93
	v_bfe_i32 v210, v208, 11, 1
	v_and_b32_e32 v92, v92, v209
	v_exp_f32_e32 v94, v94
	v_bfe_i32 v211, v208, 16, 1
	v_and_b32_e32 v93, v93, v210
	v_exp_f32_e32 v95, v95
	v_bfe_i32 v209, v208, 17, 1
	v_and_b32_e32 v94, v94, v211
	v_exp_f32_e32 v96, v96
	v_bfe_i32 v210, v208, 18, 1
	v_and_b32_e32 v95, v95, v209
	v_exp_f32_e32 v97, v97
	v_bfe_i32 v211, v208, 19, 1
	v_and_b32_e32 v96, v96, v210
	v_exp_f32_e32 v98, v98
	v_bfe_i32 v209, v208, 24, 1
	v_and_b32_e32 v97, v97, v211
	v_exp_f32_e32 v99, v99
	v_bfe_i32 v210, v208, 25, 1
	v_and_b32_e32 v98, v98, v209
	v_exp_f32_e32 v100, v100
	v_bfe_i32 v211, v208, 26, 1
	v_and_b32_e32 v99, v99, v210
	v_exp_f32_e32 v101, v101
	v_bfe_i32 v209, v208, 27, 1
	v_and_b32_e32 v100, v100, v211
	s_nop 0
	v_and_b32_e32 v101, v101, v209
	v_cvt_pk_bf16_f32 v208, v86, v87
	v_cvt_pk_bf16_f32 v209, v88, v89
	v_cvt_pk_bf16_f32 v210, v90, v91
	v_cvt_pk_bf16_f32 v211, v92, v93
	v_cvt_pk_bf16_f32 v212, v94, v95
	v_cvt_pk_bf16_f32 v213, v96, v97
	v_cvt_pk_bf16_f32 v214, v98, v99
	v_cvt_pk_bf16_f32 v215, v100, v101
	s_nop 1
	s_setprio 1
	s_waitcnt lgkmcnt(7)
	v_mfma_f32_32x32x16_bf16 v[54:69], v[248:251], v[208:211], v[54:69]
	v_add_f32_e32 v194, v194, v86
	v_add_f32_e32 v194, v87, v194
	s_waitcnt lgkmcnt(6)
	v_mfma_f32_32x32x16_bf16 v[54:69], v[222:225], v[212:215], v[54:69]
	v_add_f32_e32 v194, v88, v194
	v_add_f32_e32 v194, v89, v194
	s_waitcnt lgkmcnt(5)
	v_mfma_f32_32x32x16_bf16 v[38:53], v[216:219], v[208:211], v[38:53]
	v_add_f32_e32 v194, v90, v194
	v_add_f32_e32 v194, v91, v194
	s_waitcnt lgkmcnt(4)
	v_mfma_f32_32x32x16_bf16 v[38:53], v[228:231], v[212:215], v[38:53]
	v_add_f32_e32 v194, v92, v194
	v_add_f32_e32 v194, v93, v194
	s_waitcnt lgkmcnt(3)
	v_mfma_f32_32x32x16_bf16 v[22:37], v[232:235], v[208:211], v[22:37]
	v_add_f32_e32 v194, v94, v194
	v_add_f32_e32 v194, v95, v194
	s_waitcnt lgkmcnt(2)
	v_mfma_f32_32x32x16_bf16 v[22:37], v[236:239], v[212:215], v[22:37]
	v_add_f32_e32 v194, v96, v194
	v_add_f32_e32 v194, v97, v194
	s_waitcnt lgkmcnt(1)
	v_mfma_f32_32x32x16_bf16 v[6:21], v[240:243], v[208:211], v[6:21]
	v_add_f32_e32 v194, v98, v194
	v_add_f32_e32 v194, v99, v194
	s_waitcnt lgkmcnt(0)
	v_mfma_f32_32x32x16_bf16 v[6:21], v[244:247], v[212:215], v[6:21]
	v_add_f32_e32 v194, v100, v194
	v_add_f32_e32 v194, v101, v194
	s_setprio 0
	s_branch .Ldsa_J1
.Ldsa_B1:
	ds_read_b64 v[220:221], v206
	v_add_u32_e32 v207, v202, v180
	ds_read_b128 v[216:219], v207 offset:36864
	ds_read_b128 v[228:231], v207 offset:36896
	ds_read_b128 v[232:235], v207 offset:36928
	ds_read_b128 v[236:239], v207 offset:36960
	ds_read_b128 v[240:243], v207 offset:36992
	ds_read_b128 v[244:247], v207 offset:37024
	ds_read_b128 v[248:251], v207 offset:37056
	ds_read_b128 v[222:225], v207 offset:37088
	s_setprio 1
	s_waitcnt lgkmcnt(7)
	v_mfma_f32_32x32x16_bf16 v[102:117], v[216:219], v[126:129], v[70:85]
	ds_read_b128 v[216:219], v207 offset:45568
	s_waitcnt lgkmcnt(7)
	v_mfma_f32_32x32x16_bf16 v[102:117], v[228:231], v[0:3], v[102:117]
	ds_read_b128 v[228:231], v207 offset:45600
	s_waitcnt lgkmcnt(7)
	v_mfma_f32_32x32x16_bf16 v[102:117], v[232:235], v[118:121], v[102:117]
	ds_read_b128 v[232:235], v207 offset:45632
	s_waitcnt lgkmcnt(7)
	v_mfma_f32_32x32x16_bf16 v[102:117], v[236:239], v[122:125], v[102:117]
	ds_read_b128 v[236:239], v207 offset:45664
	s_waitcnt lgkmcnt(7)
	v_mfma_f32_32x32x16_bf16 v[102:117], v[240:243], v[130:133], v[102:117]
	ds_read_b128 v[240:243], v207 offset:45696
	s_waitcnt lgkmcnt(7)
	v_mfma_f32_32x32x16_bf16 v[102:117], v[244:247], v[134:137], v[102:117]
	ds_read_b128 v[244:247], v207 offset:45728
	s_waitcnt lgkmcnt(7)
	v_mfma_f32_32x32x16_bf16 v[102:117], v[248:251], v[138:141], v[102:117]
	ds_read_b128 v[248:251], v207 offset:45760
	s_waitcnt lgkmcnt(7)
; #define LAS __attribute__((address_space(3)))
; __device__ __forceinline__ unsigned pk2(float lo, float hi) { f32x2_t v = {lo, hi}; bf16x2_t b = __builtin_convertvector(v, bf16x2_t); return __builtin_bit_cast(unsigned, b); }
; __device__ __forceinline__ void dsa_unit32(const Args& a, LAS unsigned char* lds, const LAS unsigned long long* maskl, int b, int qb, int tid, int wave, int lane) {
;     ...
;     auto compute = [&](int buf, int kt) {
;         const unsigned long long mw = maskl[l31 * 32 + kt];
;         const LAS bf16* Ks = (const LAS bf16*)(lds + buf * STG); const LAS bf16* Vs = (const LAS bf16*)(lds + buf * STG + KBYTES);
;         f32x16 S2[2];
; #pragma unroll
;         for (int kh = 0; kh < 2; ++kh) {
; #pragma unroll
;             for (int i = 0; i < 16; ++i) S2[kh][i] = negB;
;             __builtin_amdgcn_s_setprio(1);
; #pragma unroll
;             for (int ks = 0; ks < 8; ++ks) S2[kh] = mfma32(*(const LAS bf16x8*)(Ks + (32 * kh + l31) * KS + 16 * ks + 8 * hi), qf[ks], S2[kh]);
;             __builtin_amdgcn_s_setprio(0);
;         }
; #pragma unroll
;         for (int kh = 0; kh < 2; ++kh) {
;             const unsigned mh = (unsigned)(mw >> (32 * kh + 4 * hi));
;             float p[16];
; #pragma unroll
;             for (int i = 0; i < 16; ++i) { const float e = __builtin_amdgcn_exp2f(S2[kh][i]);
;                 const int keep = __builtin_amdgcn_sbfe((int)mh, 8 * (i >> 2) + (i & 3), 1);
;                 p[i] = __builtin_bit_cast(float, __builtin_bit_cast(int, e) & keep); l += p[i]; }
;             u32x4 w0, w1;
;             w0.x = pk2(p[0], p[1]); w0.y = pk2(p[2], p[3]); w0.z = pk2(p[4], p[5]); w0.w = pk2(p[6], p[7]);
;             w1.x = pk2(p[8], p[9]); w1.y = pk2(p[10], p[11]); w1.z = pk2(p[12], p[13]); w1.w = pk2(p[14], p[15]);
;             const bf16x8 pa = __builtin_bit_cast(bf16x8, w0), pb = __builtin_bit_cast(bf16x8, w1);
;             __builtin_amdgcn_s_setprio(1);
; #pragma unroll
;             for (int ct = 0; ct < 4; ++ct) {
;                 const LAS bf16* vr = Vs + (32 * ct + l31) * VS + 4 * hi + 32 * kh;
;                 O[ct] = mfma32(cat8(*(const LAS u32x2*)(vr), *(const LAS u32x2*)(vr + 8)), pa, O[ct]);
;                 O[ct] = mfma32(cat8(*(const LAS u32x2*)(vr + 16), *(const LAS u32x2*)(vr + 24)), pb, O[ct]);
;             }
;             __builtin_amdgcn_s_setprio(0);
;         }
;     };
	v_mfma_f32_32x32x16_bf16 v[102:117], v[222:225], v[142:145], v[102:117]
	ds_read_b128 v[222:225], v207 offset:45792
	s_setprio 0
	s_nop 7
	s_nop 3
	v_lshrrev_b64 v[208:209], v182, v[220:221]
	v_exp_f32_e32 v102, v102
	v_bfe_i32 v209, v208, 0, 1
	v_exp_f32_e32 v103, v103
	v_bfe_i32 v210, v208, 1, 1
	v_and_b32_e32 v102, v102, v209
	v_exp_f32_e32 v104, v104
	v_bfe_i32 v211, v208, 2, 1
	v_and_b32_e32 v103, v103, v210
	v_exp_f32_e32 v105, v105
	v_bfe_i32 v209, v208, 3, 1
	v_and_b32_e32 v104, v104, v211
	v_exp_f32_e32 v106, v106
	v_bfe_i32 v210, v208, 8, 1
	v_and_b32_e32 v105, v105, v209
	v_exp_f32_e32 v107, v107
	v_bfe_i32 v211, v208, 9, 1
	v_and_b32_e32 v106, v106, v210
	v_exp_f32_e32 v108, v108
	v_bfe_i32 v209, v208, 10, 1
	v_and_b32_e32 v107, v107, v211
	v_exp_f32_e32 v109, v109
	v_bfe_i32 v210, v208, 11, 1
	v_and_b32_e32 v108, v108, v209
	v_exp_f32_e32 v110, v110
	v_bfe_i32 v211, v208, 16, 1
	v_and_b32_e32 v109, v109, v210
	v_exp_f32_e32 v111, v111
	v_bfe_i32 v209, v208, 17, 1
	v_and_b32_e32 v110, v110, v211
	v_exp_f32_e32 v112, v112
	v_bfe_i32 v210, v208, 18, 1
	v_and_b32_e32 v111, v111, v209
	v_exp_f32_e32 v113, v113
	v_bfe_i32 v211, v208, 19, 1
	v_and_b32_e32 v112, v112, v210
	v_exp_f32_e32 v114, v114
	v_bfe_i32 v209, v208, 24, 1
	v_and_b32_e32 v113, v113, v211
	v_exp_f32_e32 v115, v115
	v_bfe_i32 v210, v208, 25, 1
	v_and_b32_e32 v114, v114, v209
	v_exp_f32_e32 v116, v116
	v_bfe_i32 v211, v208, 26, 1
	v_and_b32_e32 v115, v115, v210
	v_exp_f32_e32 v117, v117
	v_bfe_i32 v209, v208, 27, 1
	v_and_b32_e32 v116, v116, v211
	s_nop 0
	v_and_b32_e32 v117, v117, v209
	v_cvt_pk_bf16_f32 v208, v102, v103
	v_cvt_pk_bf16_f32 v209, v104, v105
	v_cvt_pk_bf16_f32 v210, v106, v107
	v_cvt_pk_bf16_f32 v211, v108, v109
	v_cvt_pk_bf16_f32 v212, v110, v111
	v_cvt_pk_bf16_f32 v213, v112, v113
	v_cvt_pk_bf16_f32 v214, v114, v115
	v_cvt_pk_bf16_f32 v215, v116, v117
	s_setprio 1
	s_waitcnt lgkmcnt(7)
	v_mfma_f32_32x32x16_bf16 v[86:101], v[216:219], v[126:129], v[70:85]
	ds_read_b128 v[216:219], v204 offset:0
	s_waitcnt lgkmcnt(7)
	v_mfma_f32_32x32x16_bf16 v[86:101], v[228:231], v[0:3], v[86:101]
	ds_read_b128 v[228:231], v204 offset:32
	s_waitcnt lgkmcnt(7)
	v_mfma_f32_32x32x16_bf16 v[86:101], v[232:235], v[118:121], v[86:101]
	ds_read_b128 v[232:235], v204 offset:4608
	s_waitcnt lgkmcnt(7)
	v_mfma_f32_32x32x16_bf16 v[86:101], v[236:239], v[122:125], v[86:101]
	ds_read_b128 v[236:239], v204 offset:4640
	s_waitcnt lgkmcnt(7)
	v_mfma_f32_32x32x16_bf16 v[86:101], v[240:243], v[130:133], v[86:101]
	ds_read_b128 v[240:243], v204 offset:9216
	s_waitcnt lgkmcnt(7)
	v_mfma_f32_32x32x16_bf16 v[86:101], v[244:247], v[134:137], v[86:101]
	ds_read_b128 v[244:247], v204 offset:9248
	s_waitcnt lgkmcnt(7)
	v_mfma_f32_32x32x16_bf16 v[86:101], v[248:251], v[138:141], v[86:101]
	ds_read_b128 v[248:251], v204 offset:13824
	s_waitcnt lgkmcnt(7)
; #define LAS __attribute__((address_space(3)))
; __device__ __forceinline__ unsigned pk2(float lo, float hi) { f32x2_t v = {lo, hi}; bf16x2_t b = __builtin_convertvector(v, bf16x2_t); return __builtin_bit_cast(unsigned, b); }
; __device__ __forceinline__ f32x16 mfma32(bf16x8 a, bf16x8 b, f32x16 c) { return __builtin_amdgcn_mfma_f32_32x32x16_bf16(a, b, c, 0, 0, 0); }
; __device__ __forceinline__ void dsa_unit32(const Args& a, LAS unsigned char* lds, const LAS unsigned long long* maskl, int b, int qb, int tid, int wave, int lane) {
;     ...
;         for (int kh = 0; kh < 2; ++kh) {
;             const unsigned mh = (unsigned)(mw >> (32 * kh + 4 * hi));
;             float p[16];
; #pragma unroll
;             for (int i = 0; i < 16; ++i) { const float e = __builtin_amdgcn_exp2f(S2[kh][i]);
;                 const int keep = __builtin_amdgcn_sbfe((int)mh, 8 * (i >> 2) + (i & 3), 1);
;                 p[i] = __builtin_bit_cast(float, __builtin_bit_cast(int, e) & keep); l += p[i]; }
;             u32x4 w0, w1;
;             w0.x = pk2(p[0], p[1]); w0.y = pk2(p[2], p[3]); w0.z = pk2(p[4], p[5]); w0.w = pk2(p[6], p[7]);
;             w1.x = pk2(p[8], p[9]); w1.y = pk2(p[10], p[11]); w1.z = pk2(p[12], p[13]); w1.w = pk2(p[14], p[15]);
;             const bf16x8 pa = __builtin_bit_cast(bf16x8, w0), pb = __builtin_bit_cast(bf16x8, w1);
;             __builtin_amdgcn_s_setprio(1);
; #pragma unroll
;             for (int ct = 0; ct < 4; ++ct) {
;                 const LAS bf16* vr = Vs + (32 * ct + l31) * VS + 4 * hi + 32 * kh;
;                 O[ct] = mfma32(cat8(*(const LAS u32x2*)(vr), *(const LAS u32x2*)(vr + 8)), pa, O[ct]);
;                 O[ct] = mfma32(cat8(*(const LAS u32x2*)(vr + 16), *(const LAS u32x2*)(vr + 24)), pb, O[ct]);
;             }
;             __builtin_amdgcn_s_setprio(0);
;         }
	v_mfma_f32_32x32x16_bf16 v[86:101], v[222:225], v[142:145], v[86:101]
	ds_read_b128 v[222:225], v204 offset:13856
	s_setprio 0
	v_add_f32_e32 v194, v194, v102
	v_add_f32_e32 v194, v103, v194
	v_add_f32_e32 v194, v104, v194
	v_add_f32_e32 v194, v105, v194
	v_add_f32_e32 v194, v106, v194
	v_add_f32_e32 v194, v107, v194
	v_add_f32_e32 v194, v108, v194
	v_add_f32_e32 v194, v109, v194
	v_add_f32_e32 v194, v110, v194
	v_add_f32_e32 v194, v111, v194
	v_add_f32_e32 v194, v112, v194
	v_add_f32_e32 v194, v113, v194
	v_add_f32_e32 v194, v114, v194
	v_add_f32_e32 v194, v115, v194
	v_add_f32_e32 v194, v116, v194
	v_add_f32_e32 v194, v117, v194
	v_lshrrev_b64 v[110:111], v184, v[220:221]
	v_exp_f32_e32 v86, v86
	v_bfe_i32 v111, v110, 0, 1
	v_exp_f32_e32 v87, v87
	v_bfe_i32 v112, v110, 1, 1
	v_and_b32_e32 v86, v86, v111
	v_exp_f32_e32 v88, v88
	v_bfe_i32 v113, v110, 2, 1
	v_and_b32_e32 v87, v87, v112
	v_exp_f32_e32 v89, v89
	v_bfe_i32 v111, v110, 3, 1
	v_and_b32_e32 v88, v88, v113
	v_exp_f32_e32 v90, v90
	v_bfe_i32 v112, v110, 8, 1
	v_and_b32_e32 v89, v89, v111
	v_exp_f32_e32 v91, v91
	v_bfe_i32 v113, v110, 9, 1
	v_and_b32_e32 v90, v90, v112
	v_exp_f32_e32 v92, v92
	v_bfe_i32 v111, v110, 10, 1
	v_and_b32_e32 v91, v91, v113
	v_exp_f32_e32 v93, v93
	v_bfe_i32 v112, v110, 11, 1
	v_and_b32_e32 v92, v92, v111
	v_exp_f32_e32 v94, v94
	v_bfe_i32 v113, v110, 16, 1
	v_and_b32_e32 v93, v93, v112
	v_exp_f32_e32 v95, v95
	v_bfe_i32 v111, v110, 17, 1
	v_and_b32_e32 v94, v94, v113
	v_exp_f32_e32 v96, v96
	v_bfe_i32 v112, v110, 18, 1
	v_and_b32_e32 v95, v95, v111
	v_exp_f32_e32 v97, v97
	v_bfe_i32 v113, v110, 19, 1
	v_and_b32_e32 v96, v96, v112
	v_exp_f32_e32 v98, v98
	v_bfe_i32 v111, v110, 24, 1
	v_and_b32_e32 v97, v97, v113
	v_exp_f32_e32 v99, v99
	v_bfe_i32 v112, v110, 25, 1
	v_and_b32_e32 v98, v98, v111
	v_exp_f32_e32 v100, v100
	v_bfe_i32 v113, v110, 26, 1
	v_and_b32_e32 v99, v99, v112
	v_exp_f32_e32 v101, v101
	v_bfe_i32 v111, v110, 27, 1
	v_and_b32_e32 v100, v100, v113
	s_nop 0
	v_and_b32_e32 v101, v101, v111
	v_cvt_pk_bf16_f32 v102, v86, v87
	v_cvt_pk_bf16_f32 v103, v88, v89
	v_cvt_pk_bf16_f32 v104, v90, v91
	v_cvt_pk_bf16_f32 v105, v92, v93
	v_cvt_pk_bf16_f32 v106, v94, v95
	v_cvt_pk_bf16_f32 v107, v96, v97
	v_cvt_pk_bf16_f32 v108, v98, v99
	v_cvt_pk_bf16_f32 v109, v100, v101
	s_nop 1
	s_setprio 1
	s_waitcnt lgkmcnt(7)
	v_mfma_f32_32x32x16_bf16 v[54:69], v[216:219], v[208:211], v[54:69]
	ds_read_b128 v[216:219], v204 offset:64
	s_waitcnt lgkmcnt(7)
	v_mfma_f32_32x32x16_bf16 v[54:69], v[228:231], v[212:215], v[54:69]
	ds_read_b128 v[228:231], v204 offset:96
	s_waitcnt lgkmcnt(7)
	v_mfma_f32_32x32x16_bf16 v[38:53], v[232:235], v[208:211], v[38:53]
	ds_read_b128 v[232:235], v204 offset:4672
	s_waitcnt lgkmcnt(7)
	v_mfma_f32_32x32x16_bf16 v[38:53], v[236:239], v[212:215], v[38:53]
	ds_read_b128 v[236:239], v204 offset:4704
	s_waitcnt lgkmcnt(7)
	v_mfma_f32_32x32x16_bf16 v[22:37], v[240:243], v[208:211], v[22:37]
	ds_read_b128 v[240:243], v204 offset:9280
	s_waitcnt lgkmcnt(7)
	v_mfma_f32_32x32x16_bf16 v[22:37], v[244:247], v[212:215], v[22:37]
	ds_read_b128 v[244:247], v204 offset:9312
	s_waitcnt lgkmcnt(7)
	v_mfma_f32_32x32x16_bf16 v[6:21], v[248:251], v[208:211], v[6:21]
	ds_read_b128 v[248:251], v204 offset:13888
	s_waitcnt lgkmcnt(7)
	v_mfma_f32_32x32x16_bf16 v[6:21], v[222:225], v[212:215], v[6:21]
	ds_read_b128 v[222:225], v204 offset:13920
	s_waitcnt lgkmcnt(7)
	v_mfma_f32_32x32x16_bf16 v[54:69], v[216:219], v[102:105], v[54:69]
	v_add_f32_e32 v194, v194, v86
	v_add_f32_e32 v194, v87, v194
	s_waitcnt lgkmcnt(6)
	v_mfma_f32_32x32x16_bf16 v[54:69], v[228:231], v[106:109], v[54:69]
	v_add_f32_e32 v194, v88, v194
	v_add_f32_e32 v194, v89, v194
	s_waitcnt lgkmcnt(5)
	v_mfma_f32_32x32x16_bf16 v[38:53], v[232:235], v[102:105], v[38:53]
	v_add_f32_e32 v194, v90, v194
	v_add_f32_e32 v194, v91, v194
	s_waitcnt lgkmcnt(4)
	v_mfma_f32_32x32x16_bf16 v[38:53], v[236:239], v[106:109], v[38:53]
	v_add_f32_e32 v194, v92, v194
	v_add_f32_e32 v194, v93, v194
	s_waitcnt lgkmcnt(3)
	v_mfma_f32_32x32x16_bf16 v[22:37], v[240:243], v[102:105], v[22:37]
	v_add_f32_e32 v194, v94, v194
	v_add_f32_e32 v194, v95, v194
	s_waitcnt lgkmcnt(2)
	v_mfma_f32_32x32x16_bf16 v[22:37], v[244:247], v[106:109], v[22:37]
	v_add_f32_e32 v194, v96, v194
	v_add_f32_e32 v194, v97, v194
	s_waitcnt lgkmcnt(1)
	v_mfma_f32_32x32x16_bf16 v[6:21], v[248:251], v[102:105], v[6:21]
	v_add_f32_e32 v194, v98, v194
	v_add_f32_e32 v194, v99, v194
	s_waitcnt lgkmcnt(0)
	v_mfma_f32_32x32x16_bf16 v[6:21], v[222:225], v[106:109], v[6:21]
	v_add_f32_e32 v194, v100, v194
	v_add_f32_e32 v194, v101, v194
	s_setprio 0
.Ldsa_J1:
	s_andn2_b64 vcc, exec, s[0:1]
	s_cbranch_vccnz .LBB0_1301
	s_waitcnt vmcnt(3)
	ds_write_b128 v196, v[146:149]
	s_waitcnt vmcnt(1)
	ds_write2_b64 v198, v[154:155], v[156:157] offset1:2
	ds_write_b128 v199, v[150:153]
	s_waitcnt vmcnt(0)
	ds_write2_b64 v201, v[158:159], v[160:161] offset1:2
	s_branch .LBB0_1301
